# v26 + K-loop heads aligned to 64 bytes (.p2align 6)
# speedup vs baseline: 1.0500x; 1.0500x over previous
; #define PG8_STAGE(bufoff, gbase, voff) do { _Pragma("unroll") for (int _i = 0; _i < 2; ++_i) \
;         __builtin_amdgcn_global_load_lds((const unsigned*)((const char*)(gbase) + (voff)[_i]), (PG8_LAS unsigned*)(lds + (bufoff) + ldsw + _i * 8192), 16, 0, 0); } while (0)
; #define PG8_LDA(dst, b, h) do { _Pragma("unroll") for (int m = 0; m < 4; ++m) _Pragma("unroll") for (int k = 0; k < 2; ++k) dst[m][k] = *(const PG8_LAS bf16x8*)(lds + PG8_SA(b, h) + aoff + m * 2048 + k * 1024); } while (0)
; #define PG8_LDB(dst, b, h) do { _Pragma("unroll") for (int n = 0; n < 2; ++n) _Pragma("unroll") for (int k = 0; k < 2; ++k) dst[n][k] = *(const PG8_LAS bf16x8*)(lds + PG8_SB(b, h) + boff + n * 2048 + k * 1024); } while (0)
; #define PG8_WAIT_V(n) asm volatile("s_waitcnt vmcnt(" #n ")" ::: "memory")
; #define PG8_WAIT_L(n) asm volatile("s_waitcnt lgkmcnt(" #n ")" ::: "memory")
; #define PG8_BAR __builtin_amdgcn_s_barrier()
; #define PG8_SCHED __builtin_amdgcn_sched_barrier(0)
; template <class Epi, class Sched, bool ALIGN_EPI = false, bool SP2 = false, bool AGM = false  >
; __device__ __forceinline__ void gemm_phase(PG8_LAS unsigned char* lds, const Gemm g, const Sched& S, const Epi& E) {
;     ...
;         const bool has_next = S.next(ui + 1, nxt);
;         const char* nA = has_next ? (const char*)g.A + (size_t)nxt.pm * tstepA : cA; const char* nB = has_next ? (const char*)g.Bt + (size_t)nxt.pn * tstep : cB;
;         for (int t = 0; t < nt; t += 2) {
;             const bool last = (t == nt - 2);
;             const char* a1 = cA + (size_t)(t + 1) * kstepA;
;             const char* a2 = last ? nA : cA + (size_t)(t + 2) * kstepA; const char* b2 = last ? nB : cB + (size_t)(t + 2) * kstep;
;             const char* a3 = a2 + kstepA; const char* b3 = b2 + kstep;
;             if (last && has_next) S.a_ready(nxt);
;             if constexpr (SP2) {
;             PG8_LDB(B0, 0, 0); PG8_LDB(B1, 0, 1); PG8_SCHED; PG8_LDA(At, 0, 0); PG8_STAGE(PG8_SA(1, 1), a1 + hstepA, voffA);
;             PG8_WAIT_V(8); PG8_WAIT_L(0); PG8_BAR; PG8_MMA(0, 0, At, B0); PG8_MMA(0, 1, At, B1); PG8_BAR; PG8_SCHED;
;             PG8_LDA(At, 0, 1); PG8_STAGE(PG8_SB(0, 0), b2, voffB); PG8_STAGE(PG8_SB(0, 1), b2 + hstep, voffB); PG8_STAGE(PG8_SA(0, 0), a2, voffA);
;             PG8_WAIT_V(8); PG8_WAIT_L(0); PG8_BAR; PG8_MMA(1, 0, At, B0); PG8_MMA(1, 1, At, B1); PG8_BAR; PG8_SCHED;
.LBB0_136:
	s_ashr_i32 s15, s14, 31
	s_lshl_b64 s[16:17], s[14:15], 19
	s_add_u32 s16, s46, s16
	s_addc_u32 s17, s47, s17
	s_and_b64 s[18:19], s[0:1], exec
	s_cselect_b32 s15, s17, s23
	s_cselect_b32 s21, s16, s22
	s_ashr_i32 s13, s12, 31
	s_lshl_b64 s[18:19], s[12:13], 19
	s_add_u32 s18, s3, s18
	s_addc_u32 s19, s28, s19
	s_and_b64 s[26:27], s[0:1], exec
	s_cselect_b32 s13, s19, s25
	s_cselect_b32 s45, s18, s24
	s_add_u32 s22, s22, 0x40080
	s_addc_u32 s23, s23, 0
	s_add_u32 s53, s24, 0x100
	s_addc_u32 s54, s25, 0
	s_mov_b32 s55, -2
	ds_read_b128 v[150:153], v160
	ds_read_b128 v[164:167], v160 offset:1024
	ds_read_b128 v[168:171], v160 offset:2048
	ds_read_b128 v[172:175], v160 offset:3072
	ds_read_b128 v[176:179], v161
	ds_read_b128 v[180:183], v161 offset:1024
	ds_read_b128 v[184:187], v161 offset:2048
	ds_read_b128 v[188:191], v161 offset:3072
	s_add_u32 s24, s22, 0xfffc0080
	s_addc_u32 s25, s23, -1
	s_cmp_eq_u32 s55, 12
	s_cselect_b32 s27, s15, s25
	s_cselect_b32 s26, s21, s24
	s_cselect_b32 s25, s13, s54
	s_cselect_b32 s24, s45, s53
	v_lshl_add_u64 v[224:225], s[22:23], 0, v[142:143]
	s_add_i32 m0, s33, 0xc000
	ds_read_b128 v[192:195], v162
	ds_read_b128 v[196:199], v162 offset:1024
	ds_read_b128 v[200:203], v162 offset:2048
	ds_read_b128 v[204:207], v162 offset:3072
	ds_read_b128 v[208:211], v162 offset:4096
	ds_read_b128 v[212:215], v162 offset:5120
	ds_read_b128 v[216:219], v162 offset:6144
	ds_read_b128 v[220:223], v162 offset:7168
	global_load_lds_dwordx4 v[224:225], off
	v_lshl_add_u64 v[224:225], s[22:23], 0, v[144:145]
	s_add_i32 m0, s33, 0xe000
	s_nop 0
	global_load_lds_dwordx4 v[224:225], off
	s_waitcnt vmcnt(8)
	s_waitcnt lgkmcnt(0)
	s_barrier
	s_setprio 1
	s_waitcnt lgkmcnt(0)
	v_mfma_f32_16x16x32_bf16 v[126:129], v[150:153], v[192:195], 0
	v_mfma_f32_16x16x32_bf16 v[122:125], v[168:171], v[192:195], 0
	v_mfma_f32_16x16x32_bf16 v[114:117], v[150:153], v[200:203], 0
	v_mfma_f32_16x16x32_bf16 v[106:109], v[168:171], v[200:203], 0
	v_mfma_f32_16x16x32_bf16 v[102:105], v[150:153], v[208:211], 0
	v_mfma_f32_16x16x32_bf16 v[94:97], v[168:171], v[208:211], 0
	v_mfma_f32_16x16x32_bf16 v[86:89], v[150:153], v[216:219], 0
	v_mfma_f32_16x16x32_bf16 v[78:81], v[168:171], v[216:219], 0
	v_mfma_f32_16x16x32_bf16 v[126:129], v[164:167], v[196:199], v[126:129]
	v_mfma_f32_16x16x32_bf16 v[122:125], v[172:175], v[196:199], v[122:125]
	v_mfma_f32_16x16x32_bf16 v[114:117], v[164:167], v[204:207], v[114:117]
	v_mfma_f32_16x16x32_bf16 v[106:109], v[172:175], v[204:207], v[106:109]
	v_mfma_f32_16x16x32_bf16 v[102:105], v[164:167], v[212:215], v[102:105]
	v_mfma_f32_16x16x32_bf16 v[94:97], v[172:175], v[212:215], v[94:97]
	v_mfma_f32_16x16x32_bf16 v[86:89], v[164:167], v[220:223], v[86:89]
	v_mfma_f32_16x16x32_bf16 v[78:81], v[172:175], v[220:223], v[78:81]
	s_setprio 0
	s_setprio 1
	v_mfma_f32_16x16x32_bf16 v[118:121], v[176:179], v[192:195], 0
	v_mfma_f32_16x16x32_bf16 v[110:113], v[184:187], v[192:195], 0
	v_mfma_f32_16x16x32_bf16 v[98:101], v[176:179], v[200:203], 0
	v_mfma_f32_16x16x32_bf16 v[90:93], v[184:187], v[200:203], 0
	v_mfma_f32_16x16x32_bf16 v[82:85], v[176:179], v[208:211], 0
	v_mfma_f32_16x16x32_bf16 v[74:77], v[184:187], v[208:211], 0
	v_mfma_f32_16x16x32_bf16 v[70:73], v[176:179], v[216:219], 0
	v_mfma_f32_16x16x32_bf16 v[66:69], v[184:187], v[216:219], 0
	v_mfma_f32_16x16x32_bf16 v[118:121], v[180:183], v[196:199], v[118:121]
	v_mfma_f32_16x16x32_bf16 v[110:113], v[188:191], v[196:199], v[110:113]
	v_mfma_f32_16x16x32_bf16 v[98:101], v[180:183], v[204:207], v[98:101]
	v_mfma_f32_16x16x32_bf16 v[90:93], v[188:191], v[204:207], v[90:93]
	v_mfma_f32_16x16x32_bf16 v[82:85], v[180:183], v[212:215], v[82:85]
	v_mfma_f32_16x16x32_bf16 v[74:77], v[188:191], v[212:215], v[74:77]
	v_mfma_f32_16x16x32_bf16 v[70:73], v[180:183], v[220:223], v[70:73]
	v_mfma_f32_16x16x32_bf16 v[66:69], v[188:191], v[220:223], v[66:69]
	s_setprio 0
	s_barrier
	s_add_i32 s58, s41, s29
	v_lshl_add_u64 v[224:225], s[24:25], 0, v[134:135]
	s_mov_b32 m0, s58
	ds_read_b128 v[192:195], v162 offset:16384
	ds_read_b128 v[196:199], v162 offset:17408
	ds_read_b128 v[200:203], v162 offset:18432
	ds_read_b128 v[204:207], v162 offset:19456
	ds_read_b128 v[208:211], v162 offset:20480
	ds_read_b128 v[212:215], v162 offset:21504
	ds_read_b128 v[216:219], v162 offset:22528
	ds_read_b128 v[220:223], v162 offset:23552
	global_load_lds_dwordx4 v[224:225], off
	s_add_i32 m0, s58, 0x2000
	s_add_u32 s58, s24, 0x40000
	v_lshl_add_u64 v[226:227], s[24:25], 0, v[130:131]
	s_addc_u32 s59, s25, 0
	s_add_i32 s60, s42, s29
	global_load_lds_dwordx4 v[226:227], off
	v_lshl_add_u64 v[228:229], s[58:59], 0, v[134:135]
	s_mov_b32 m0, s60
	v_lshl_add_u64 v[230:231], s[26:27], 0, v[132:133]
	global_load_lds_dwordx4 v[228:229], off
	v_lshl_add_u64 v[228:229], s[58:59], 0, v[130:131]
	s_add_i32 m0, s60, 0x2000
	s_nop 0
	global_load_lds_dwordx4 v[228:229], off
	v_lshl_add_u64 v[228:229], s[26:27], 0, v[136:137]
	s_mov_b32 m0, s33
	s_nop 0
	global_load_lds_dwordx4 v[228:229], off
	s_mov_b32 m0, s34
	s_nop 0
	global_load_lds_dwordx4 v[230:231], off
	s_waitcnt vmcnt(8)
	s_waitcnt lgkmcnt(0)
	s_barrier
; #define PG8_STAGE(bufoff, gbase, voff) do { _Pragma("unroll") for (int _i = 0; _i < 2; ++_i) \
;         __builtin_amdgcn_global_load_lds((const unsigned*)((const char*)(gbase) + (voff)[_i]), (PG8_LAS unsigned*)(lds + (bufoff) + ldsw + _i * 8192), 16, 0, 0); } while (0)
; #define PG8_LDA(dst, b, h) do { _Pragma("unroll") for (int m = 0; m < 4; ++m) _Pragma("unroll") for (int k = 0; k < 2; ++k) dst[m][k] = *(const PG8_LAS bf16x8*)(lds + PG8_SA(b, h) + aoff + m * 2048 + k * 1024); } while (0)
; #define PG8_LDB(dst, b, h) do { _Pragma("unroll") for (int n = 0; n < 2; ++n) _Pragma("unroll") for (int k = 0; k < 2; ++k) dst[n][k] = *(const PG8_LAS bf16x8*)(lds + PG8_SB(b, h) + boff + n * 2048 + k * 1024); } while (0)
; #define PG8_MMA(ai, bj, At, Bt) do { __builtin_amdgcn_s_setprio(1); _Pragma("unroll") for (int m = 0; m < 4; ++m) _Pragma("unroll") for (int n = 0; n < 2; ++n) _Pragma("unroll") for (int k = 0; k < 2; ++k) \
;         acc[ai][bj][m][n] = __builtin_amdgcn_mfma_f32_16x16x32_bf16(Bt[n][k], At[m][k], acc[ai][bj][m][n], 0, 0, 0); __builtin_amdgcn_s_setprio(0); } while (0)
; #define PG8_WAIT_V(n) asm volatile("s_waitcnt vmcnt(" #n ")" ::: "memory")
; #define PG8_WAIT_L(n) asm volatile("s_waitcnt lgkmcnt(" #n ")" ::: "memory")
; #define PG8_BAR __builtin_amdgcn_s_barrier()
; #define PG8_SCHED __builtin_amdgcn_sched_barrier(0)
; template <class Epi, class Sched, bool ALIGN_EPI = false, bool SP2 = false, bool AGM = false  >
; __device__ __forceinline__ void gemm_phase(PG8_LAS unsigned char* lds, const Gemm g, const Sched& S, const Epi& E) {
;     ...
;             PG8_WAIT_V(8); PG8_WAIT_L(0); PG8_BAR; PG8_MMA(1, 0, At, B0); PG8_MMA(1, 1, At, B1); PG8_BAR; PG8_SCHED;
;             PG8_LDB(B0, 1, 0); PG8_LDB(B1, 1, 1); PG8_SCHED; PG8_LDA(At, 1, 0); PG8_STAGE(PG8_SA(0, 1), a2 + hstepA, voffA);
;             PG8_WAIT_V(8); PG8_WAIT_L(0); PG8_BAR; PG8_MMA(0, 0, At, B0); PG8_MMA(0, 1, At, B1); PG8_BAR; PG8_SCHED;
;             PG8_LDA(At, 1, 1); PG8_STAGE(PG8_SB(1, 0), b3, voffB); PG8_STAGE(PG8_SB(1, 1), b3 + hstep, voffB); PG8_STAGE(PG8_SA(1, 0), a3, voffA);
	s_setprio 1
	s_waitcnt lgkmcnt(0)
	v_mfma_f32_16x16x32_bf16 v[62:65], v[150:153], v[192:195], 0
	v_mfma_f32_16x16x32_bf16 v[58:61], v[168:171], v[192:195], 0
	v_mfma_f32_16x16x32_bf16 v[54:57], v[150:153], v[200:203], 0
	v_mfma_f32_16x16x32_bf16 v[46:49], v[168:171], v[200:203], 0
	v_mfma_f32_16x16x32_bf16 v[38:41], v[150:153], v[208:211], 0
	v_mfma_f32_16x16x32_bf16 v[30:33], v[168:171], v[208:211], 0
	v_mfma_f32_16x16x32_bf16 v[22:25], v[150:153], v[216:219], 0
	v_mfma_f32_16x16x32_bf16 v[14:17], v[168:171], v[216:219], 0
	v_mfma_f32_16x16x32_bf16 v[62:65], v[164:167], v[196:199], v[62:65]
	v_mfma_f32_16x16x32_bf16 v[58:61], v[172:175], v[196:199], v[58:61]
	v_mfma_f32_16x16x32_bf16 v[54:57], v[164:167], v[204:207], v[54:57]
	v_mfma_f32_16x16x32_bf16 v[46:49], v[172:175], v[204:207], v[46:49]
	v_mfma_f32_16x16x32_bf16 v[38:41], v[164:167], v[212:215], v[38:41]
	v_mfma_f32_16x16x32_bf16 v[30:33], v[172:175], v[212:215], v[30:33]
	v_mfma_f32_16x16x32_bf16 v[22:25], v[164:167], v[220:223], v[22:25]
	v_mfma_f32_16x16x32_bf16 v[14:17], v[172:175], v[220:223], v[14:17]
	s_setprio 0
	s_setprio 1
	v_mfma_f32_16x16x32_bf16 v[50:53], v[176:179], v[192:195], 0
	v_mfma_f32_16x16x32_bf16 v[42:45], v[184:187], v[192:195], 0
	v_mfma_f32_16x16x32_bf16 v[34:37], v[176:179], v[200:203], 0
	v_mfma_f32_16x16x32_bf16 v[26:29], v[184:187], v[200:203], 0
	v_mfma_f32_16x16x32_bf16 v[18:21], v[176:179], v[208:211], 0
	v_mfma_f32_16x16x32_bf16 v[10:13], v[184:187], v[208:211], 0
	v_mfma_f32_16x16x32_bf16 v[6:9], v[176:179], v[216:219], 0
	v_mfma_f32_16x16x32_bf16 v[2:5], v[184:187], v[216:219], 0
	v_mfma_f32_16x16x32_bf16 v[50:53], v[180:183], v[196:199], v[50:53]
	v_mfma_f32_16x16x32_bf16 v[42:45], v[188:191], v[196:199], v[42:45]
	v_mfma_f32_16x16x32_bf16 v[34:37], v[180:183], v[204:207], v[34:37]
	v_mfma_f32_16x16x32_bf16 v[26:29], v[188:191], v[204:207], v[26:29]
	v_mfma_f32_16x16x32_bf16 v[18:21], v[180:183], v[212:215], v[18:21]
	v_mfma_f32_16x16x32_bf16 v[10:13], v[188:191], v[212:215], v[10:13]
	v_mfma_f32_16x16x32_bf16 v[6:9], v[180:183], v[220:223], v[6:9]
	v_mfma_f32_16x16x32_bf16 v[2:5], v[188:191], v[220:223], v[2:5]
	s_setprio 0
	s_barrier
	s_add_i32 s58, 0, 0x18000
	v_add_u32_e32 v138, s58, v157
	s_add_i32 s59, 0, 0x1c000
	ds_read_b128 v[150:153], v138
	ds_read_b128 v[164:167], v138 offset:1024
	ds_read_b128 v[168:171], v138 offset:2048
	ds_read_b128 v[172:175], v138 offset:3072
	v_add_u32_e32 v138, s59, v157
	ds_read_b128 v[176:179], v138
	ds_read_b128 v[180:183], v138 offset:1024
	ds_read_b128 v[184:187], v138 offset:2048
	ds_read_b128 v[188:191], v138 offset:3072
	s_add_u32 s26, s26, 0x40000
	s_addc_u32 s27, s27, 0
	s_mov_b32 m0, s35
	v_lshl_add_u64 v[232:233], s[26:27], 0, v[136:137]
	ds_read_b128 v[192:195], v162 offset:32768
	ds_read_b128 v[196:199], v162 offset:33792
	ds_read_b128 v[200:203], v162 offset:34816
	ds_read_b128 v[204:207], v162 offset:35840
	ds_read_b128 v[208:211], v162 offset:36864
	ds_read_b128 v[212:215], v162 offset:37888
	ds_read_b128 v[216:219], v162 offset:38912
	ds_read_b128 v[220:223], v162 offset:39936
	global_load_lds_dwordx4 v[232:233], off
	v_lshl_add_u64 v[232:233], s[26:27], 0, v[132:133]
	s_mov_b32 m0, s36
	s_nop 0
	global_load_lds_dwordx4 v[232:233], off
	s_waitcnt vmcnt(8)
	s_waitcnt lgkmcnt(0)
	s_barrier
	s_setprio 1
	s_waitcnt lgkmcnt(0)
	v_mfma_f32_16x16x32_bf16 v[126:129], v[150:153], v[192:195], v[126:129]
	v_mfma_f32_16x16x32_bf16 v[122:125], v[168:171], v[192:195], v[122:125]
	v_mfma_f32_16x16x32_bf16 v[114:117], v[150:153], v[200:203], v[114:117]
	v_mfma_f32_16x16x32_bf16 v[106:109], v[168:171], v[200:203], v[106:109]
	v_mfma_f32_16x16x32_bf16 v[102:105], v[150:153], v[208:211], v[102:105]
	v_mfma_f32_16x16x32_bf16 v[94:97], v[168:171], v[208:211], v[94:97]
	v_mfma_f32_16x16x32_bf16 v[86:89], v[150:153], v[216:219], v[86:89]
	v_mfma_f32_16x16x32_bf16 v[78:81], v[168:171], v[216:219], v[78:81]
	v_mfma_f32_16x16x32_bf16 v[126:129], v[164:167], v[196:199], v[126:129]
	v_mfma_f32_16x16x32_bf16 v[122:125], v[172:175], v[196:199], v[122:125]
	v_mfma_f32_16x16x32_bf16 v[114:117], v[164:167], v[204:207], v[114:117]
	v_mfma_f32_16x16x32_bf16 v[106:109], v[172:175], v[204:207], v[106:109]
	v_mfma_f32_16x16x32_bf16 v[102:105], v[164:167], v[212:215], v[102:105]
	v_mfma_f32_16x16x32_bf16 v[94:97], v[172:175], v[212:215], v[94:97]
	v_mfma_f32_16x16x32_bf16 v[86:89], v[164:167], v[220:223], v[86:89]
	v_mfma_f32_16x16x32_bf16 v[78:81], v[172:175], v[220:223], v[78:81]
	s_setprio 0
	s_setprio 1
	v_mfma_f32_16x16x32_bf16 v[118:121], v[176:179], v[192:195], v[118:121]
	v_mfma_f32_16x16x32_bf16 v[110:113], v[184:187], v[192:195], v[110:113]
	v_mfma_f32_16x16x32_bf16 v[98:101], v[176:179], v[200:203], v[98:101]
	v_mfma_f32_16x16x32_bf16 v[90:93], v[184:187], v[200:203], v[90:93]
	v_mfma_f32_16x16x32_bf16 v[82:85], v[176:179], v[208:211], v[82:85]
	v_mfma_f32_16x16x32_bf16 v[74:77], v[184:187], v[208:211], v[74:77]
	v_mfma_f32_16x16x32_bf16 v[70:73], v[176:179], v[216:219], v[70:73]
	v_mfma_f32_16x16x32_bf16 v[66:69], v[184:187], v[216:219], v[66:69]
	v_mfma_f32_16x16x32_bf16 v[118:121], v[180:183], v[196:199], v[118:121]
	v_mfma_f32_16x16x32_bf16 v[110:113], v[188:191], v[196:199], v[110:113]
	v_mfma_f32_16x16x32_bf16 v[98:101], v[180:183], v[204:207], v[98:101]
	v_mfma_f32_16x16x32_bf16 v[90:93], v[188:191], v[204:207], v[90:93]
	v_mfma_f32_16x16x32_bf16 v[82:85], v[180:183], v[212:215], v[82:85]
	v_mfma_f32_16x16x32_bf16 v[74:77], v[188:191], v[212:215], v[74:77]
	v_mfma_f32_16x16x32_bf16 v[70:73], v[180:183], v[220:223], v[70:73]
	v_mfma_f32_16x16x32_bf16 v[66:69], v[188:191], v[220:223], v[66:69]
	s_setprio 0
	s_barrier
; #define PG8_STAGE(bufoff, gbase, voff) do { _Pragma("unroll") for (int _i = 0; _i < 2; ++_i) \
;         __builtin_amdgcn_global_load_lds((const unsigned*)((const char*)(gbase) + (voff)[_i]), (PG8_LAS unsigned*)(lds + (bufoff) + ldsw + _i * 8192), 16, 0, 0); } while (0)
; #define PG8_LDA(dst, b, h) do { _Pragma("unroll") for (int m = 0; m < 4; ++m) _Pragma("unroll") for (int k = 0; k < 2; ++k) dst[m][k] = *(const PG8_LAS bf16x8*)(lds + PG8_SA(b, h) + aoff + m * 2048 + k * 1024); } while (0)
; #define PG8_MMA(ai, bj, At, Bt) do { __builtin_amdgcn_s_setprio(1); _Pragma("unroll") for (int m = 0; m < 4; ++m) _Pragma("unroll") for (int n = 0; n < 2; ++n) _Pragma("unroll") for (int k = 0; k < 2; ++k) \
;         acc[ai][bj][m][n] = __builtin_amdgcn_mfma_f32_16x16x32_bf16(Bt[n][k], At[m][k], acc[ai][bj][m][n], 0, 0, 0); __builtin_amdgcn_s_setprio(0); } while (0)
; #define PG8_WAIT_V(n) asm volatile("s_waitcnt vmcnt(" #n ")" ::: "memory")
; #define PG8_WAIT_L(n) asm volatile("s_waitcnt lgkmcnt(" #n ")" ::: "memory")
; #define PG8_BAR __builtin_amdgcn_s_barrier()
; #define PG8_SCHED __builtin_amdgcn_sched_barrier(0)
; template <class Epi, class Sched, bool ALIGN_EPI = false, bool SP2 = false, bool AGM = false  >
; __device__ __forceinline__ void gemm_phase(PG8_LAS unsigned char* lds, const Gemm g, const Sched& S, const Epi& E) {
;     ...
;         for (int t = 0; t < nt; t += 2) {
;     ...
;             PG8_LDA(At, 1, 1); PG8_STAGE(PG8_SB(1, 0), b3, voffB); PG8_STAGE(PG8_SB(1, 1), b3 + hstep, voffB); PG8_STAGE(PG8_SA(1, 0), a3, voffA);
;             PG8_WAIT_V(8); PG8_WAIT_L(0); PG8_BAR; PG8_MMA(1, 0, At, B0); PG8_MMA(1, 1, At, B1); PG8_BAR; PG8_SCHED;
	s_add_i32 s26, s58, s29
	v_lshl_add_u64 v[224:225], v[224:225], 0, s[10:11]
	s_mov_b32 m0, s26
	ds_read_b128 v[192:195], v162 offset:49152
	ds_read_b128 v[196:199], v162 offset:50176
	ds_read_b128 v[200:203], v162 offset:51200
	ds_read_b128 v[204:207], v162 offset:52224
	ds_read_b128 v[208:211], v162 offset:53248
	ds_read_b128 v[212:215], v162 offset:54272
	ds_read_b128 v[216:219], v162 offset:55296
	ds_read_b128 v[220:223], v162 offset:56320
	global_load_lds_dwordx4 v[224:225], off
	s_add_i32 m0, s26, 0x2000
	s_add_u32 s24, s24, 0x40080
	v_lshl_add_u64 v[224:225], v[226:227], 0, s[10:11]
	s_addc_u32 s25, s25, 0
	s_add_i32 s26, s59, s29
	global_load_lds_dwordx4 v[224:225], off
	v_lshl_add_u64 v[224:225], s[24:25], 0, v[134:135]
	s_mov_b32 m0, s26
	s_nop 0
	global_load_lds_dwordx4 v[224:225], off
	v_lshl_add_u64 v[224:225], s[24:25], 0, v[130:131]
	s_add_i32 m0, s26, 0x2000
	s_nop 0
	global_load_lds_dwordx4 v[224:225], off
	v_lshl_add_u64 v[224:225], v[228:229], 0, s[10:11]
	s_mov_b32 m0, s38
	s_nop 0
	global_load_lds_dwordx4 v[224:225], off
	v_lshl_add_u64 v[224:225], v[230:231], 0, s[10:11]
	s_mov_b32 m0, s39
	s_nop 0
	global_load_lds_dwordx4 v[224:225], off
	s_waitcnt vmcnt(8)
	s_waitcnt lgkmcnt(0)
	s_barrier
	s_setprio 1
	s_waitcnt lgkmcnt(0)
	v_mfma_f32_16x16x32_bf16 v[62:65], v[150:153], v[192:195], v[62:65]
	v_mfma_f32_16x16x32_bf16 v[58:61], v[168:171], v[192:195], v[58:61]
	v_mfma_f32_16x16x32_bf16 v[54:57], v[150:153], v[200:203], v[54:57]
	v_mfma_f32_16x16x32_bf16 v[46:49], v[168:171], v[200:203], v[46:49]
	v_mfma_f32_16x16x32_bf16 v[38:41], v[150:153], v[208:211], v[38:41]
	v_mfma_f32_16x16x32_bf16 v[30:33], v[168:171], v[208:211], v[30:33]
	v_mfma_f32_16x16x32_bf16 v[22:25], v[150:153], v[216:219], v[22:25]
	v_mfma_f32_16x16x32_bf16 v[14:17], v[168:171], v[216:219], v[14:17]
	v_mfma_f32_16x16x32_bf16 v[62:65], v[164:167], v[196:199], v[62:65]
	v_mfma_f32_16x16x32_bf16 v[58:61], v[172:175], v[196:199], v[58:61]
	v_mfma_f32_16x16x32_bf16 v[54:57], v[164:167], v[204:207], v[54:57]
	v_mfma_f32_16x16x32_bf16 v[46:49], v[172:175], v[204:207], v[46:49]
	v_mfma_f32_16x16x32_bf16 v[38:41], v[164:167], v[212:215], v[38:41]
	v_mfma_f32_16x16x32_bf16 v[30:33], v[172:175], v[212:215], v[30:33]
	v_mfma_f32_16x16x32_bf16 v[22:25], v[164:167], v[220:223], v[22:25]
	v_mfma_f32_16x16x32_bf16 v[14:17], v[172:175], v[220:223], v[14:17]
	s_setprio 0
	s_setprio 1
	v_mfma_f32_16x16x32_bf16 v[50:53], v[176:179], v[192:195], v[50:53]
	v_mfma_f32_16x16x32_bf16 v[42:45], v[184:187], v[192:195], v[42:45]
	v_mfma_f32_16x16x32_bf16 v[34:37], v[176:179], v[200:203], v[34:37]
	v_mfma_f32_16x16x32_bf16 v[26:29], v[184:187], v[200:203], v[26:29]
	v_mfma_f32_16x16x32_bf16 v[18:21], v[176:179], v[208:211], v[18:21]
	v_mfma_f32_16x16x32_bf16 v[10:13], v[184:187], v[208:211], v[10:13]
	v_mfma_f32_16x16x32_bf16 v[6:9], v[176:179], v[216:219], v[6:9]
	v_mfma_f32_16x16x32_bf16 v[2:5], v[184:187], v[216:219], v[2:5]
	v_mfma_f32_16x16x32_bf16 v[50:53], v[180:183], v[196:199], v[50:53]
	v_mfma_f32_16x16x32_bf16 v[42:45], v[188:191], v[196:199], v[42:45]
	v_mfma_f32_16x16x32_bf16 v[34:37], v[180:183], v[204:207], v[34:37]
	v_mfma_f32_16x16x32_bf16 v[26:29], v[188:191], v[204:207], v[26:29]
	v_mfma_f32_16x16x32_bf16 v[18:21], v[180:183], v[212:215], v[18:21]
	v_mfma_f32_16x16x32_bf16 v[10:13], v[188:191], v[212:215], v[10:13]
	v_mfma_f32_16x16x32_bf16 v[6:9], v[180:183], v[220:223], v[6:9]
	v_mfma_f32_16x16x32_bf16 v[2:5], v[188:191], v[220:223], v[2:5]
	s_setprio 0
	s_barrier
	s_add_i32 s55, s55, 2
	s_add_u32 s22, s22, 0x100
	s_addc_u32 s23, s23, 0
	s_add_u32 s53, s53, 0x100
	s_addc_u32 s54, s54, 0
	s_cmp_gt_u32 s55, 13
	s_cbranch_scc1 .Lpeel_done_p1
	.p2align	6

; template <class Epi, class Sched, bool ALIGN_EPI = false, bool SP2 = false, bool AGM = false  >
; __device__ __forceinline__ void gemm_phase(PG8_LAS unsigned char* lds, const Gemm g, const Sched& S, const Epi& E) {
;     ...
;         const bool has_next = S.next(ui + 1, nxt);
;         const char* nA = has_next ? (const char*)g.A + (size_t)nxt.pm * tstepA : cA; const char* nB = has_next ? (const char*)g.Bt + (size_t)nxt.pn * tstep : cB;
;     ...
; #pragma unroll
;         for (int a = 0; a < 2; ++a)
; #pragma unroll
;             for (int b = 0; b < 2; ++b)
; #pragma unroll
;                 for (int m = 0; m < 4; ++m)
; #pragma unroll
;                     for (int n = 0; n < 2; ++n) acc[a][b][m][n] = (f32x4){0.f, 0.f, 0.f, 0.f};
;         cur = nxt; cA = nA; cB = nB; ++ui;
.LBB0_676:
	s_ashr_i32 s19, s18, 31
	s_lshl_b64 s[20:21], s[18:19], 13
	s_add_u32 s20, s64, s20
	s_addc_u32 s21, s65, s21
	s_and_b64 s[22:23], s[0:1], exec
	s_cselect_b32 s19, s21, s25
	s_cselect_b32 s62, s20, s24
	s_ashr_i32 s17, s16, 31
	s_lshl_b64 s[22:23], s[16:17], 18
	s_add_u32 s22, s3, s22
	s_addc_u32 s23, s36, s23
	s_and_b64 s[28:29], s[0:1], exec
	s_cselect_b32 s17, s23, s27
	s_cselect_b32 s63, s22, s26
	s_add_u32 s68, s26, 0x100
	v_mov_b32_e32 v2, 0
	s_addc_u32 s69, s27, 0
	s_mov_b32 s70, -2
	v_mov_b32_e32 v3, v2
	v_mov_b32_e32 v4, v2
	v_mov_b32_e32 v5, v2
	v_mov_b32_e32 v6, v2
	v_mov_b32_e32 v7, v2
	v_mov_b32_e32 v8, v2
	v_mov_b32_e32 v9, v2
	s_waitcnt vmcnt(0)
	v_mov_b32_e32 v18, v2
	v_mov_b32_e32 v19, v2
	v_mov_b32_e32 v20, v2
	v_mov_b32_e32 v21, v2
	v_mov_b32_e32 v22, v2
	v_mov_b32_e32 v23, v2
	v_mov_b32_e32 v24, v2
	v_mov_b32_e32 v25, v2
	v_mov_b32_e32 v34, v2
	v_mov_b32_e32 v35, v2
	v_mov_b32_e32 v36, v2
	v_mov_b32_e32 v37, v2
	v_mov_b32_e32 v38, v2
	v_mov_b32_e32 v39, v2
	v_mov_b32_e32 v40, v2
	v_mov_b32_e32 v41, v2
	v_mov_b32_e32 v50, v2
	v_mov_b32_e32 v51, v2
	v_mov_b32_e32 v52, v2
	v_mov_b32_e32 v53, v2
	v_mov_b32_e32 v54, v2
	v_mov_b32_e32 v55, v2
	v_mov_b32_e32 v56, v2
	v_mov_b32_e32 v57, v2
	v_mov_b32_e32 v10, v2
	v_mov_b32_e32 v11, v2
	v_mov_b32_e32 v12, v2
	v_mov_b32_e32 v13, v2
	v_mov_b32_e32 v14, v2
	v_mov_b32_e32 v15, v2
	v_mov_b32_e32 v16, v2
	v_mov_b32_e32 v17, v2
	v_mov_b32_e32 v26, v2
	v_mov_b32_e32 v27, v2
	v_mov_b32_e32 v28, v2
	v_mov_b32_e32 v29, v2
	v_mov_b32_e32 v30, v2
	v_mov_b32_e32 v31, v2
	v_mov_b32_e32 v32, v2
	v_mov_b32_e32 v33, v2
	v_mov_b32_e32 v42, v2
	v_mov_b32_e32 v43, v2
	v_mov_b32_e32 v44, v2
	v_mov_b32_e32 v45, v2
	v_mov_b32_e32 v46, v2
	v_mov_b32_e32 v47, v2
	v_mov_b32_e32 v48, v2
	v_mov_b32_e32 v49, v2
	v_mov_b32_e32 v58, v2
	v_mov_b32_e32 v59, v2
	v_mov_b32_e32 v60, v2
	v_mov_b32_e32 v61, v2
	v_mov_b32_e32 v62, v2
	v_mov_b32_e32 v63, v2
	v_mov_b32_e32 v64, v2
	v_mov_b32_e32 v65, v2
	v_mov_b32_e32 v66, v2
	v_mov_b32_e32 v67, v2
	v_mov_b32_e32 v68, v2
	v_mov_b32_e32 v69, v2
	v_mov_b32_e32 v70, v2
	v_mov_b32_e32 v71, v2
	v_mov_b32_e32 v72, v2
	v_mov_b32_e32 v73, v2
	v_mov_b32_e32 v82, v2
	v_mov_b32_e32 v83, v2
	v_mov_b32_e32 v84, v2
	v_mov_b32_e32 v85, v2
	v_mov_b32_e32 v86, v2
	v_mov_b32_e32 v87, v2
	v_mov_b32_e32 v88, v2
	v_mov_b32_e32 v89, v2
	v_mov_b32_e32 v98, v2
	v_mov_b32_e32 v99, v2
	v_mov_b32_e32 v100, v2
	v_mov_b32_e32 v101, v2
	v_mov_b32_e32 v102, v2
	v_mov_b32_e32 v103, v2
	v_mov_b32_e32 v104, v2
	v_mov_b32_e32 v105, v2
	v_mov_b32_e32 v114, v2
	v_mov_b32_e32 v115, v2
	v_mov_b32_e32 v116, v2
	v_mov_b32_e32 v117, v2
	v_mov_b32_e32 v118, v2
	v_mov_b32_e32 v119, v2
	v_mov_b32_e32 v120, v2
	v_mov_b32_e32 v121, v2
	v_mov_b32_e32 v74, v2
	v_mov_b32_e32 v75, v2
	v_mov_b32_e32 v76, v2
	v_mov_b32_e32 v77, v2
	v_mov_b32_e32 v78, v2
	v_mov_b32_e32 v79, v2
	v_mov_b32_e32 v80, v2
	v_mov_b32_e32 v81, v2
	v_mov_b32_e32 v90, v2
	v_mov_b32_e32 v91, v2
	v_mov_b32_e32 v92, v2
	v_mov_b32_e32 v93, v2
	v_mov_b32_e32 v94, v2
	v_mov_b32_e32 v95, v2
	v_mov_b32_e32 v96, v2
	v_mov_b32_e32 v97, v2
	v_mov_b32_e32 v106, v2
	v_mov_b32_e32 v107, v2
	v_mov_b32_e32 v108, v2
	v_mov_b32_e32 v109, v2
	v_mov_b32_e32 v110, v2
	v_mov_b32_e32 v111, v2
	v_mov_b32_e32 v112, v2
	v_mov_b32_e32 v113, v2
	v_mov_b32_e32 v122, v2
	v_mov_b32_e32 v123, v2
	v_mov_b32_e32 v124, v2
	v_mov_b32_e32 v125, v2
	v_mov_b32_e32 v126, v2
	v_mov_b32_e32 v127, v2
	v_mov_b32_e32 v128, v2
	v_mov_b32_e32 v129, v2
	.p2align	6

; template <class Epi, class Sched, bool ALIGN_EPI = false, bool SP2 = false, bool AGM = false  >
; __device__ __forceinline__ void gemm_phase(PG8_LAS unsigned char* lds, const Gemm g, const Sched& S, const Epi& E) {
;     ...
;         const bool has_next = S.next(ui + 1, nxt);
;         const char* nA = has_next ? (const char*)g.A + (size_t)nxt.pm * tstepA : cA; const char* nB = has_next ? (const char*)g.Bt + (size_t)nxt.pn * tstep : cB;
;     ...
; #pragma unroll
;         for (int a = 0; a < 2; ++a)
; #pragma unroll
;             for (int b = 0; b < 2; ++b)
; #pragma unroll
;                 for (int m = 0; m < 4; ++m)
; #pragma unroll
;                     for (int n = 0; n < 2; ++n) acc[a][b][m][n] = (f32x4){0.f, 0.f, 0.f, 0.f};
;         cur = nxt; cA = nA; cB = nB; ++ui;
.LBB0_782:
	s_ashr_i32 s31, s30, 31
	s_lshl_b64 s[34:35], s[30:31], 19
	s_add_u32 s34, s8, s34
	s_addc_u32 s35, s9, s35
	s_and_b64 s[36:37], s[6:7], exec
	s_cselect_b32 s5, s35, s39
	s_cselect_b32 s31, s34, s38
	s_ashr_i32 s29, s28, 31
	s_lshl_b64 s[36:37], s[28:29], 19
	s_add_u32 s36, s14, s36
	s_addc_u32 s37, s15, s37
	s_and_b64 s[42:43], s[6:7], exec
	s_cselect_b32 s29, s37, s41
	s_cselect_b32 s33, s36, s40
	s_add_u32 s38, s38, 0x40080
	s_addc_u32 s39, s39, 0
	s_add_u32 s62, s40, 0x100
	v_mov_b32_e32 v2, 0
	s_addc_u32 s74, s41, 0
	s_mov_b32 s75, -2
	v_mov_b32_e32 v3, v2
	s_waitcnt lgkmcnt(0)
	v_mov_b32_e32 v4, v2
	v_mov_b32_e32 v5, v2
	v_mov_b32_e32 v6, v2
	v_mov_b32_e32 v7, v2
	v_mov_b32_e32 v8, v2
	v_mov_b32_e32 v9, v2
	s_waitcnt vmcnt(0)
	v_mov_b32_e32 v18, v2
	v_mov_b32_e32 v19, v2
	v_mov_b32_e32 v20, v2
	v_mov_b32_e32 v21, v2
	v_mov_b32_e32 v22, v2
	v_mov_b32_e32 v23, v2
	v_mov_b32_e32 v24, v2
	v_mov_b32_e32 v25, v2
	v_mov_b32_e32 v34, v2
	v_mov_b32_e32 v35, v2
	v_mov_b32_e32 v36, v2
	v_mov_b32_e32 v37, v2
	v_mov_b32_e32 v38, v2
	v_mov_b32_e32 v39, v2
	v_mov_b32_e32 v40, v2
	v_mov_b32_e32 v41, v2
	v_mov_b32_e32 v50, v2
	v_mov_b32_e32 v51, v2
	v_mov_b32_e32 v52, v2
	v_mov_b32_e32 v53, v2
	v_mov_b32_e32 v54, v2
	v_mov_b32_e32 v55, v2
	v_mov_b32_e32 v56, v2
	v_mov_b32_e32 v57, v2
	v_mov_b32_e32 v10, v2
	v_mov_b32_e32 v11, v2
	v_mov_b32_e32 v12, v2
	v_mov_b32_e32 v13, v2
	v_mov_b32_e32 v14, v2
	v_mov_b32_e32 v15, v2
	v_mov_b32_e32 v16, v2
	v_mov_b32_e32 v17, v2
	v_mov_b32_e32 v26, v2
	v_mov_b32_e32 v27, v2
	v_mov_b32_e32 v28, v2
	v_mov_b32_e32 v29, v2
	v_mov_b32_e32 v30, v2
	v_mov_b32_e32 v31, v2
	v_mov_b32_e32 v32, v2
	v_mov_b32_e32 v33, v2
	v_mov_b32_e32 v42, v2
	v_mov_b32_e32 v43, v2
	v_mov_b32_e32 v44, v2
	v_mov_b32_e32 v45, v2
	v_mov_b32_e32 v46, v2
	v_mov_b32_e32 v47, v2
	v_mov_b32_e32 v48, v2
	v_mov_b32_e32 v49, v2
	v_mov_b32_e32 v58, v2
	v_mov_b32_e32 v59, v2
	v_mov_b32_e32 v60, v2
	v_mov_b32_e32 v61, v2
	v_mov_b32_e32 v62, v2
	v_mov_b32_e32 v63, v2
	v_mov_b32_e32 v64, v2
	v_mov_b32_e32 v65, v2
	v_mov_b32_e32 v66, v2
	v_mov_b32_e32 v67, v2
	v_mov_b32_e32 v68, v2
	v_mov_b32_e32 v69, v2
	v_mov_b32_e32 v70, v2
	v_mov_b32_e32 v71, v2
	v_mov_b32_e32 v72, v2
	v_mov_b32_e32 v73, v2
	v_mov_b32_e32 v82, v2
	v_mov_b32_e32 v83, v2
	v_mov_b32_e32 v84, v2
	v_mov_b32_e32 v85, v2
	v_mov_b32_e32 v86, v2
	v_mov_b32_e32 v87, v2
	v_mov_b32_e32 v88, v2
	v_mov_b32_e32 v89, v2
	v_mov_b32_e32 v98, v2
	v_mov_b32_e32 v99, v2
	v_mov_b32_e32 v100, v2
	v_mov_b32_e32 v101, v2
	v_mov_b32_e32 v102, v2
	v_mov_b32_e32 v103, v2
	v_mov_b32_e32 v104, v2
	v_mov_b32_e32 v105, v2
	v_mov_b32_e32 v114, v2
	v_mov_b32_e32 v115, v2
	v_mov_b32_e32 v116, v2
	v_mov_b32_e32 v117, v2
	v_mov_b32_e32 v118, v2
	v_mov_b32_e32 v119, v2
	v_mov_b32_e32 v120, v2
	v_mov_b32_e32 v121, v2
	v_mov_b32_e32 v74, v2
	v_mov_b32_e32 v75, v2
	v_mov_b32_e32 v76, v2
	v_mov_b32_e32 v77, v2
	v_mov_b32_e32 v78, v2
	v_mov_b32_e32 v79, v2
	v_mov_b32_e32 v80, v2
	v_mov_b32_e32 v81, v2
	v_mov_b32_e32 v90, v2
	v_mov_b32_e32 v91, v2
	v_mov_b32_e32 v92, v2
	v_mov_b32_e32 v93, v2
	v_mov_b32_e32 v94, v2
	v_mov_b32_e32 v95, v2
	v_mov_b32_e32 v96, v2
	v_mov_b32_e32 v97, v2
	v_mov_b32_e32 v106, v2
	v_mov_b32_e32 v107, v2
	v_mov_b32_e32 v108, v2
	v_mov_b32_e32 v109, v2
	v_mov_b32_e32 v110, v2
	v_mov_b32_e32 v111, v2
	v_mov_b32_e32 v112, v2
	v_mov_b32_e32 v113, v2
	v_mov_b32_e32 v122, v2
	v_mov_b32_e32 v123, v2
	v_mov_b32_e32 v124, v2
	v_mov_b32_e32 v125, v2
	v_mov_b32_e32 v126, v2
	v_mov_b32_e32 v127, v2
	v_mov_b32_e32 v128, v2
	v_mov_b32_e32 v129, v2
	.p2align	6

; #define PG8_STAGE(bufoff, gbase, voff) do { _Pragma("unroll") for (int _i = 0; _i < 2; ++_i) \
;         __builtin_amdgcn_global_load_lds((const unsigned*)((const char*)(gbase) + (voff)[_i]), (PG8_LAS unsigned*)(lds + (bufoff) + ldsw + _i * 8192), 16, 0, 0); } while (0)
; #define PG8_LDA(dst, b, h) do { _Pragma("unroll") for (int m = 0; m < 4; ++m) _Pragma("unroll") for (int k = 0; k < 2; ++k) dst[m][k] = *(const PG8_LAS bf16x8*)(lds + PG8_SA(b, h) + aoff + m * 2048 + k * 1024); } while (0)
; #define PG8_LDB(dst, b, h) do { _Pragma("unroll") for (int n = 0; n < 2; ++n) _Pragma("unroll") for (int k = 0; k < 2; ++k) dst[n][k] = *(const PG8_LAS bf16x8*)(lds + PG8_SB(b, h) + boff + n * 2048 + k * 1024); } while (0)
; #define PG8_MMA(ai, bj, At, Bt) do { __builtin_amdgcn_s_setprio(1); _Pragma("unroll") for (int m = 0; m < 4; ++m) _Pragma("unroll") for (int n = 0; n < 2; ++n) _Pragma("unroll") for (int k = 0; k < 2; ++k) \
;         acc[ai][bj][m][n] = __builtin_amdgcn_mfma_f32_16x16x32_bf16(Bt[n][k], At[m][k], acc[ai][bj][m][n], 0, 0, 0); __builtin_amdgcn_s_setprio(0); } while (0)
; template <class Epi, class Sched, bool ALIGN_EPI = false, bool SP2 = false, bool AGM = false  >
; __device__ __forceinline__ void gemm_phase(PG8_LAS unsigned char* lds, const Gemm g, const Sched& S, const Epi& E) {
;     ...
;         const bool has_next = S.next(ui + 1, nxt);
;         const char* nA = has_next ? (const char*)g.A + (size_t)nxt.pm * tstepA : cA; const char* nB = has_next ? (const char*)g.Bt + (size_t)nxt.pn * tstep : cB;
;         for (int t = 0; t < nt; t += 2) {
;             const bool last = (t == nt - 2);
;             const char* a1 = cA + (size_t)(t + 1) * kstepA;
;             const char* a2 = last ? nA : cA + (size_t)(t + 2) * kstepA; const char* b2 = last ? nB : cB + (size_t)(t + 2) * kstep;
;             const char* a3 = a2 + kstepA; const char* b3 = b2 + kstep;
;             if (last && has_next) S.a_ready(nxt);
;             if constexpr (SP2) {
;             PG8_LDB(B0, 0, 0); PG8_LDB(B1, 0, 1); PG8_SCHED; PG8_LDA(At, 0, 0); PG8_STAGE(PG8_SA(1, 1), a1 + hstepA, voffA);
;             PG8_WAIT_V(8); PG8_WAIT_L(0); PG8_BAR; PG8_MMA(0, 0, At, B0); PG8_MMA(0, 1, At, B1); PG8_BAR; PG8_SCHED;
;             PG8_LDA(At, 0, 1); PG8_STAGE(PG8_SB(0, 0), b2, voffB); PG8_STAGE(PG8_SB(0, 1), b2 + hstep, voffB); PG8_STAGE(PG8_SA(0, 0), a2, voffA);
.LBB0_876:
	s_ashr_i32 s23, s22, 31
	s_lshl_b64 s[24:25], s[22:23], 19
	s_add_u32 s24, s46, s24
	s_addc_u32 s25, s47, s25
	s_and_b64 s[26:27], s[0:1], exec
	s_cselect_b32 s23, s25, s29
	s_cselect_b32 s64, s24, s28
	s_ashr_i32 s21, s20, 31
	s_lshl_b64 s[26:27], s[20:21], 19
	s_add_u32 s26, s10, s26
	s_addc_u32 s27, s11, s27
	s_and_b64 s[34:35], s[0:1], exec
	s_cselect_b32 s21, s27, s31
	s_cselect_b32 s65, s26, s30
	s_add_u32 s28, s28, 0x40080
	s_addc_u32 s29, s29, 0
	s_add_u32 s66, s30, 0x100
	s_addc_u32 s67, s31, 0
	s_mov_b32 s68, -2
	s_waitcnt vmcnt(0)
	s_waitcnt lgkmcnt(0)
	ds_read_b128 v[148:151], v156
	ds_read_b128 v[164:167], v156 offset:1024
	ds_read_b128 v[168:171], v156 offset:2048
	ds_read_b128 v[172:175], v156 offset:3072
	ds_read_b128 v[176:179], v157
	ds_read_b128 v[180:183], v157 offset:1024
	ds_read_b128 v[184:187], v157 offset:2048
	ds_read_b128 v[188:191], v157 offset:3072
	s_add_u32 s30, s28, 0xfffc0080
	s_addc_u32 s31, s29, -1
	s_cmp_eq_u32 s68, 12
	s_cselect_b32 s35, s23, s31
	s_cselect_b32 s34, s64, s30
	s_cselect_b32 s31, s21, s67
	s_cselect_b32 s30, s65, s66
	v_lshl_add_u64 v[224:225], s[28:29], 0, v[140:141]
	s_add_i32 m0, s37, 0xc000
	ds_read_b128 v[192:195], v158
	ds_read_b128 v[196:199], v158 offset:1024
	ds_read_b128 v[200:203], v158 offset:2048
	ds_read_b128 v[204:207], v158 offset:3072
	ds_read_b128 v[208:211], v158 offset:4096
	ds_read_b128 v[212:215], v158 offset:5120
	ds_read_b128 v[216:219], v158 offset:6144
	ds_read_b128 v[220:223], v158 offset:7168
	global_load_lds_dwordx4 v[224:225], off
	v_lshl_add_u64 v[224:225], s[28:29], 0, v[142:143]
	s_add_i32 m0, s37, 0xe000
	s_nop 0
	global_load_lds_dwordx4 v[224:225], off
	s_waitcnt vmcnt(8)
	s_waitcnt lgkmcnt(0)
	s_barrier
	s_setprio 1
	s_waitcnt lgkmcnt(0)
	v_mfma_f32_16x16x32_bf16 v[126:129], v[148:151], v[192:195], 0
	v_mfma_f32_16x16x32_bf16 v[122:125], v[168:171], v[192:195], 0
	v_mfma_f32_16x16x32_bf16 v[110:113], v[148:151], v[200:203], 0
	v_mfma_f32_16x16x32_bf16 v[106:109], v[168:171], v[200:203], 0
	v_mfma_f32_16x16x32_bf16 v[94:97], v[148:151], v[208:211], 0
	v_mfma_f32_16x16x32_bf16 v[90:93], v[168:171], v[208:211], 0
	v_mfma_f32_16x16x32_bf16 v[78:81], v[148:151], v[216:219], 0
	v_mfma_f32_16x16x32_bf16 v[74:77], v[168:171], v[216:219], 0
	v_mfma_f32_16x16x32_bf16 v[126:129], v[164:167], v[196:199], v[126:129]
	v_mfma_f32_16x16x32_bf16 v[122:125], v[172:175], v[196:199], v[122:125]
	v_mfma_f32_16x16x32_bf16 v[110:113], v[164:167], v[204:207], v[110:113]
	v_mfma_f32_16x16x32_bf16 v[106:109], v[172:175], v[204:207], v[106:109]
	v_mfma_f32_16x16x32_bf16 v[94:97], v[164:167], v[212:215], v[94:97]
	v_mfma_f32_16x16x32_bf16 v[90:93], v[172:175], v[212:215], v[90:93]
	v_mfma_f32_16x16x32_bf16 v[78:81], v[164:167], v[220:223], v[78:81]
	v_mfma_f32_16x16x32_bf16 v[74:77], v[172:175], v[220:223], v[74:77]
	s_setprio 0
	s_setprio 1
	v_mfma_f32_16x16x32_bf16 v[118:121], v[176:179], v[192:195], 0
	v_mfma_f32_16x16x32_bf16 v[114:117], v[184:187], v[192:195], 0
	v_mfma_f32_16x16x32_bf16 v[102:105], v[176:179], v[200:203], 0
	v_mfma_f32_16x16x32_bf16 v[98:101], v[184:187], v[200:203], 0
	v_mfma_f32_16x16x32_bf16 v[86:89], v[176:179], v[208:211], 0
	v_mfma_f32_16x16x32_bf16 v[82:85], v[184:187], v[208:211], 0
	v_mfma_f32_16x16x32_bf16 v[70:73], v[176:179], v[216:219], 0
	v_mfma_f32_16x16x32_bf16 v[66:69], v[184:187], v[216:219], 0
	v_mfma_f32_16x16x32_bf16 v[118:121], v[180:183], v[196:199], v[118:121]
	v_mfma_f32_16x16x32_bf16 v[114:117], v[188:191], v[196:199], v[114:117]
	v_mfma_f32_16x16x32_bf16 v[102:105], v[180:183], v[204:207], v[102:105]
	v_mfma_f32_16x16x32_bf16 v[98:101], v[188:191], v[204:207], v[98:101]
	v_mfma_f32_16x16x32_bf16 v[86:89], v[180:183], v[212:215], v[86:89]
	v_mfma_f32_16x16x32_bf16 v[82:85], v[188:191], v[212:215], v[82:85]
	v_mfma_f32_16x16x32_bf16 v[70:73], v[180:183], v[220:223], v[70:73]
	v_mfma_f32_16x16x32_bf16 v[66:69], v[188:191], v[220:223], v[66:69]
	s_setprio 0
	s_barrier
	s_add_i32 s69, s53, s3
	v_lshl_add_u64 v[224:225], s[30:31], 0, v[134:135]
	s_mov_b32 m0, s69
	ds_read_b128 v[192:195], v158 offset:16384
	ds_read_b128 v[196:199], v158 offset:17408
	ds_read_b128 v[200:203], v158 offset:18432
	ds_read_b128 v[204:207], v158 offset:19456
	ds_read_b128 v[208:211], v158 offset:20480
	ds_read_b128 v[212:215], v158 offset:21504
	ds_read_b128 v[216:219], v158 offset:22528
	ds_read_b128 v[220:223], v158 offset:23552
	global_load_lds_dwordx4 v[224:225], off
	s_add_i32 m0, s69, 0x2000
	s_add_u32 s70, s30, 0x40000
	v_lshl_add_u64 v[226:227], s[30:31], 0, v[130:131]
	s_addc_u32 s71, s31, 0
	s_add_i32 s69, s54, s3
	global_load_lds_dwordx4 v[226:227], off
	v_lshl_add_u64 v[228:229], s[70:71], 0, v[134:135]
	s_mov_b32 m0, s69
	v_lshl_add_u64 v[230:231], s[34:35], 0, v[132:133]
	global_load_lds_dwordx4 v[228:229], off
	v_lshl_add_u64 v[228:229], s[70:71], 0, v[130:131]
	s_add_i32 m0, s69, 0x2000
	s_nop 0
	global_load_lds_dwordx4 v[228:229], off
	v_lshl_add_u64 v[228:229], s[34:35], 0, v[136:137]
	s_mov_b32 m0, s37
	s_nop 0
	global_load_lds_dwordx4 v[228:229], off
	s_mov_b32 m0, s38
	s_nop 0
	global_load_lds_dwordx4 v[230:231], off
	s_waitcnt vmcnt(8)
	s_waitcnt lgkmcnt(0)
	s_barrier
; #define PG8_STAGE(bufoff, gbase, voff) do { _Pragma("unroll") for (int _i = 0; _i < 2; ++_i) \
;         __builtin_amdgcn_global_load_lds((const unsigned*)((const char*)(gbase) + (voff)[_i]), (PG8_LAS unsigned*)(lds + (bufoff) + ldsw + _i * 8192), 16, 0, 0); } while (0)
; #define PG8_LDA(dst, b, h) do { _Pragma("unroll") for (int m = 0; m < 4; ++m) _Pragma("unroll") for (int k = 0; k < 2; ++k) dst[m][k] = *(const PG8_LAS bf16x8*)(lds + PG8_SA(b, h) + aoff + m * 2048 + k * 1024); } while (0)
; #define PG8_LDB(dst, b, h) do { _Pragma("unroll") for (int n = 0; n < 2; ++n) _Pragma("unroll") for (int k = 0; k < 2; ++k) dst[n][k] = *(const PG8_LAS bf16x8*)(lds + PG8_SB(b, h) + boff + n * 2048 + k * 1024); } while (0)
; #define PG8_MMA(ai, bj, At, Bt) do { __builtin_amdgcn_s_setprio(1); _Pragma("unroll") for (int m = 0; m < 4; ++m) _Pragma("unroll") for (int n = 0; n < 2; ++n) _Pragma("unroll") for (int k = 0; k < 2; ++k) \
;         acc[ai][bj][m][n] = __builtin_amdgcn_mfma_f32_16x16x32_bf16(Bt[n][k], At[m][k], acc[ai][bj][m][n], 0, 0, 0); __builtin_amdgcn_s_setprio(0); } while (0)
; #define PG8_WAIT_V(n) asm volatile("s_waitcnt vmcnt(" #n ")" ::: "memory")
; #define PG8_WAIT_L(n) asm volatile("s_waitcnt lgkmcnt(" #n ")" ::: "memory")
; #define PG8_BAR __builtin_amdgcn_s_barrier()
; #define PG8_SCHED __builtin_amdgcn_sched_barrier(0)
; template <class Epi, class Sched, bool ALIGN_EPI = false, bool SP2 = false, bool AGM = false  >
; __device__ __forceinline__ void gemm_phase(PG8_LAS unsigned char* lds, const Gemm g, const Sched& S, const Epi& E) {
;     ...
;             PG8_LDA(At, 0, 1); PG8_STAGE(PG8_SB(0, 0), b2, voffB); PG8_STAGE(PG8_SB(0, 1), b2 + hstep, voffB); PG8_STAGE(PG8_SA(0, 0), a2, voffA);
;             PG8_WAIT_V(8); PG8_WAIT_L(0); PG8_BAR; PG8_MMA(1, 0, At, B0); PG8_MMA(1, 1, At, B1); PG8_BAR; PG8_SCHED;
;             PG8_LDB(B0, 1, 0); PG8_LDB(B1, 1, 1); PG8_SCHED; PG8_LDA(At, 1, 0); PG8_STAGE(PG8_SA(0, 1), a2 + hstepA, voffA);
;             PG8_WAIT_V(8); PG8_WAIT_L(0); PG8_BAR; PG8_MMA(0, 0, At, B0); PG8_MMA(0, 1, At, B1); PG8_BAR; PG8_SCHED;
	s_setprio 1
	s_waitcnt lgkmcnt(0)
	v_mfma_f32_16x16x32_bf16 v[62:65], v[148:151], v[192:195], 0
	v_mfma_f32_16x16x32_bf16 v[58:61], v[168:171], v[192:195], 0
	v_mfma_f32_16x16x32_bf16 v[46:49], v[148:151], v[200:203], 0
	v_mfma_f32_16x16x32_bf16 v[42:45], v[168:171], v[200:203], 0
	v_mfma_f32_16x16x32_bf16 v[30:33], v[148:151], v[208:211], 0
	v_mfma_f32_16x16x32_bf16 v[26:29], v[168:171], v[208:211], 0
	v_mfma_f32_16x16x32_bf16 v[14:17], v[148:151], v[216:219], 0
	v_mfma_f32_16x16x32_bf16 v[10:13], v[168:171], v[216:219], 0
	v_mfma_f32_16x16x32_bf16 v[62:65], v[164:167], v[196:199], v[62:65]
	v_mfma_f32_16x16x32_bf16 v[58:61], v[172:175], v[196:199], v[58:61]
	v_mfma_f32_16x16x32_bf16 v[46:49], v[164:167], v[204:207], v[46:49]
	v_mfma_f32_16x16x32_bf16 v[42:45], v[172:175], v[204:207], v[42:45]
	v_mfma_f32_16x16x32_bf16 v[30:33], v[164:167], v[212:215], v[30:33]
	v_mfma_f32_16x16x32_bf16 v[26:29], v[172:175], v[212:215], v[26:29]
	v_mfma_f32_16x16x32_bf16 v[14:17], v[164:167], v[220:223], v[14:17]
	v_mfma_f32_16x16x32_bf16 v[10:13], v[172:175], v[220:223], v[10:13]
	s_setprio 0
	s_setprio 1
	v_mfma_f32_16x16x32_bf16 v[54:57], v[176:179], v[192:195], 0
	v_mfma_f32_16x16x32_bf16 v[50:53], v[184:187], v[192:195], 0
	v_mfma_f32_16x16x32_bf16 v[38:41], v[176:179], v[200:203], 0
	v_mfma_f32_16x16x32_bf16 v[34:37], v[184:187], v[200:203], 0
	v_mfma_f32_16x16x32_bf16 v[22:25], v[176:179], v[208:211], 0
	v_mfma_f32_16x16x32_bf16 v[18:21], v[184:187], v[208:211], 0
	v_mfma_f32_16x16x32_bf16 v[6:9], v[176:179], v[216:219], 0
	v_mfma_f32_16x16x32_bf16 v[2:5], v[184:187], v[216:219], 0
	v_mfma_f32_16x16x32_bf16 v[54:57], v[180:183], v[196:199], v[54:57]
	v_mfma_f32_16x16x32_bf16 v[50:53], v[188:191], v[196:199], v[50:53]
	v_mfma_f32_16x16x32_bf16 v[38:41], v[180:183], v[204:207], v[38:41]
	v_mfma_f32_16x16x32_bf16 v[34:37], v[188:191], v[204:207], v[34:37]
	v_mfma_f32_16x16x32_bf16 v[22:25], v[180:183], v[212:215], v[22:25]
	v_mfma_f32_16x16x32_bf16 v[18:21], v[188:191], v[212:215], v[18:21]
	v_mfma_f32_16x16x32_bf16 v[6:9], v[180:183], v[220:223], v[6:9]
	v_mfma_f32_16x16x32_bf16 v[2:5], v[188:191], v[220:223], v[2:5]
	s_setprio 0
	s_barrier
	s_add_i32 s69, 0, 0x18000
	s_add_i32 s70, 0, 0x1c000
	v_add_u32_e32 v172, s69, v155
	v_add_u32_e32 v188, s70, v155
	ds_read_b128 v[148:151], v172
	ds_read_b128 v[164:167], v172 offset:1024
	ds_read_b128 v[168:171], v172 offset:2048
	ds_read_b128 v[172:175], v172 offset:3072
	ds_read_b128 v[176:179], v188
	ds_read_b128 v[180:183], v188 offset:1024
	ds_read_b128 v[184:187], v188 offset:2048
	ds_read_b128 v[188:191], v188 offset:3072
	s_add_u32 s34, s34, 0x40000
	s_addc_u32 s35, s35, 0
	s_mov_b32 m0, s39
	v_lshl_add_u64 v[232:233], s[34:35], 0, v[136:137]
	ds_read_b128 v[192:195], v158 offset:32768
	ds_read_b128 v[196:199], v158 offset:33792
	ds_read_b128 v[200:203], v158 offset:34816
	ds_read_b128 v[204:207], v158 offset:35840
	ds_read_b128 v[208:211], v158 offset:36864
	ds_read_b128 v[212:215], v158 offset:37888
	ds_read_b128 v[216:219], v158 offset:38912
	ds_read_b128 v[220:223], v158 offset:39936
	global_load_lds_dwordx4 v[232:233], off
	v_lshl_add_u64 v[232:233], s[34:35], 0, v[132:133]
	s_mov_b32 m0, s40
	s_nop 0
	global_load_lds_dwordx4 v[232:233], off
	s_waitcnt vmcnt(8)
	s_waitcnt lgkmcnt(0)
	s_barrier
	s_setprio 1
	s_waitcnt lgkmcnt(0)
	v_mfma_f32_16x16x32_bf16 v[126:129], v[148:151], v[192:195], v[126:129]
	v_mfma_f32_16x16x32_bf16 v[122:125], v[168:171], v[192:195], v[122:125]
	v_mfma_f32_16x16x32_bf16 v[110:113], v[148:151], v[200:203], v[110:113]
	v_mfma_f32_16x16x32_bf16 v[106:109], v[168:171], v[200:203], v[106:109]
	v_mfma_f32_16x16x32_bf16 v[94:97], v[148:151], v[208:211], v[94:97]
	v_mfma_f32_16x16x32_bf16 v[90:93], v[168:171], v[208:211], v[90:93]
	v_mfma_f32_16x16x32_bf16 v[78:81], v[148:151], v[216:219], v[78:81]
	v_mfma_f32_16x16x32_bf16 v[74:77], v[168:171], v[216:219], v[74:77]
	v_mfma_f32_16x16x32_bf16 v[126:129], v[164:167], v[196:199], v[126:129]
	v_mfma_f32_16x16x32_bf16 v[122:125], v[172:175], v[196:199], v[122:125]
	v_mfma_f32_16x16x32_bf16 v[110:113], v[164:167], v[204:207], v[110:113]
	v_mfma_f32_16x16x32_bf16 v[106:109], v[172:175], v[204:207], v[106:109]
	v_mfma_f32_16x16x32_bf16 v[94:97], v[164:167], v[212:215], v[94:97]
	v_mfma_f32_16x16x32_bf16 v[90:93], v[172:175], v[212:215], v[90:93]
	v_mfma_f32_16x16x32_bf16 v[78:81], v[164:167], v[220:223], v[78:81]
	v_mfma_f32_16x16x32_bf16 v[74:77], v[172:175], v[220:223], v[74:77]
	s_setprio 0
	s_setprio 1
	v_mfma_f32_16x16x32_bf16 v[118:121], v[176:179], v[192:195], v[118:121]
	v_mfma_f32_16x16x32_bf16 v[114:117], v[184:187], v[192:195], v[114:117]
	v_mfma_f32_16x16x32_bf16 v[102:105], v[176:179], v[200:203], v[102:105]
	v_mfma_f32_16x16x32_bf16 v[98:101], v[184:187], v[200:203], v[98:101]
	v_mfma_f32_16x16x32_bf16 v[86:89], v[176:179], v[208:211], v[86:89]
	v_mfma_f32_16x16x32_bf16 v[82:85], v[184:187], v[208:211], v[82:85]
	v_mfma_f32_16x16x32_bf16 v[70:73], v[176:179], v[216:219], v[70:73]
	v_mfma_f32_16x16x32_bf16 v[66:69], v[184:187], v[216:219], v[66:69]
	v_mfma_f32_16x16x32_bf16 v[118:121], v[180:183], v[196:199], v[118:121]
	v_mfma_f32_16x16x32_bf16 v[114:117], v[188:191], v[196:199], v[114:117]
	v_mfma_f32_16x16x32_bf16 v[102:105], v[180:183], v[204:207], v[102:105]
	v_mfma_f32_16x16x32_bf16 v[98:101], v[188:191], v[204:207], v[98:101]
	v_mfma_f32_16x16x32_bf16 v[86:89], v[180:183], v[212:215], v[86:89]
	v_mfma_f32_16x16x32_bf16 v[82:85], v[188:191], v[212:215], v[82:85]
	v_mfma_f32_16x16x32_bf16 v[70:73], v[180:183], v[220:223], v[70:73]
	v_mfma_f32_16x16x32_bf16 v[66:69], v[188:191], v[220:223], v[66:69]
	s_setprio 0
	s_barrier
; #define PG8_STAGE(bufoff, gbase, voff) do { _Pragma("unroll") for (int _i = 0; _i < 2; ++_i) \
;         __builtin_amdgcn_global_load_lds((const unsigned*)((const char*)(gbase) + (voff)[_i]), (PG8_LAS unsigned*)(lds + (bufoff) + ldsw + _i * 8192), 16, 0, 0); } while (0)
; #define PG8_LDA(dst, b, h) do { _Pragma("unroll") for (int m = 0; m < 4; ++m) _Pragma("unroll") for (int k = 0; k < 2; ++k) dst[m][k] = *(const PG8_LAS bf16x8*)(lds + PG8_SA(b, h) + aoff + m * 2048 + k * 1024); } while (0)
; #define PG8_MMA(ai, bj, At, Bt) do { __builtin_amdgcn_s_setprio(1); _Pragma("unroll") for (int m = 0; m < 4; ++m) _Pragma("unroll") for (int n = 0; n < 2; ++n) _Pragma("unroll") for (int k = 0; k < 2; ++k) \
;         acc[ai][bj][m][n] = __builtin_amdgcn_mfma_f32_16x16x32_bf16(Bt[n][k], At[m][k], acc[ai][bj][m][n], 0, 0, 0); __builtin_amdgcn_s_setprio(0); } while (0)
; #define PG8_WAIT_V(n) asm volatile("s_waitcnt vmcnt(" #n ")" ::: "memory")
; #define PG8_WAIT_L(n) asm volatile("s_waitcnt lgkmcnt(" #n ")" ::: "memory")
; #define PG8_BAR __builtin_amdgcn_s_barrier()
; #define PG8_SCHED __builtin_amdgcn_sched_barrier(0)
; template <class Epi, class Sched, bool ALIGN_EPI = false, bool SP2 = false, bool AGM = false  >
; __device__ __forceinline__ void gemm_phase(PG8_LAS unsigned char* lds, const Gemm g, const Sched& S, const Epi& E) {
;     ...
;             PG8_LDA(At, 1, 1); PG8_STAGE(PG8_SB(1, 0), b3, voffB); PG8_STAGE(PG8_SB(1, 1), b3 + hstep, voffB); PG8_STAGE(PG8_SA(1, 0), a3, voffA);
;             PG8_WAIT_V(8); PG8_WAIT_L(0); PG8_BAR; PG8_MMA(1, 0, At, B0); PG8_MMA(1, 1, At, B1); PG8_BAR; PG8_SCHED;
	s_add_i32 s34, s69, s3
	v_lshl_add_u64 v[224:225], v[224:225], 0, s[16:17]
	s_mov_b32 m0, s34
	ds_read_b128 v[192:195], v158 offset:49152
	ds_read_b128 v[196:199], v158 offset:50176
	ds_read_b128 v[200:203], v158 offset:51200
	ds_read_b128 v[204:207], v158 offset:52224
	ds_read_b128 v[208:211], v158 offset:53248
	ds_read_b128 v[212:215], v158 offset:54272
	ds_read_b128 v[216:219], v158 offset:55296
	ds_read_b128 v[220:223], v158 offset:56320
	global_load_lds_dwordx4 v[224:225], off
	s_add_i32 m0, s34, 0x2000
	s_add_u32 s30, s30, 0x40080
	v_lshl_add_u64 v[224:225], v[226:227], 0, s[16:17]
	s_addc_u32 s31, s31, 0
	s_add_i32 s34, s70, s3
	global_load_lds_dwordx4 v[224:225], off
	v_lshl_add_u64 v[224:225], s[30:31], 0, v[134:135]
	s_mov_b32 m0, s34
	s_nop 0
	global_load_lds_dwordx4 v[224:225], off
	v_lshl_add_u64 v[224:225], s[30:31], 0, v[130:131]
	s_add_i32 m0, s34, 0x2000
	s_nop 0
	global_load_lds_dwordx4 v[224:225], off
	v_lshl_add_u64 v[224:225], v[228:229], 0, s[16:17]
	s_mov_b32 m0, s43
	s_nop 0
	global_load_lds_dwordx4 v[224:225], off
	v_lshl_add_u64 v[224:225], v[230:231], 0, s[16:17]
	s_mov_b32 m0, s44
	s_nop 0
	global_load_lds_dwordx4 v[224:225], off
	s_waitcnt vmcnt(8)
	s_waitcnt lgkmcnt(0)
	s_barrier
	s_setprio 1
	s_waitcnt lgkmcnt(0)
	v_mfma_f32_16x16x32_bf16 v[62:65], v[148:151], v[192:195], v[62:65]
	v_mfma_f32_16x16x32_bf16 v[58:61], v[168:171], v[192:195], v[58:61]
	v_mfma_f32_16x16x32_bf16 v[46:49], v[148:151], v[200:203], v[46:49]
	v_mfma_f32_16x16x32_bf16 v[42:45], v[168:171], v[200:203], v[42:45]
	v_mfma_f32_16x16x32_bf16 v[30:33], v[148:151], v[208:211], v[30:33]
	v_mfma_f32_16x16x32_bf16 v[26:29], v[168:171], v[208:211], v[26:29]
	v_mfma_f32_16x16x32_bf16 v[14:17], v[148:151], v[216:219], v[14:17]
	v_mfma_f32_16x16x32_bf16 v[10:13], v[168:171], v[216:219], v[10:13]
	v_mfma_f32_16x16x32_bf16 v[62:65], v[164:167], v[196:199], v[62:65]
	v_mfma_f32_16x16x32_bf16 v[58:61], v[172:175], v[196:199], v[58:61]
	v_mfma_f32_16x16x32_bf16 v[46:49], v[164:167], v[204:207], v[46:49]
	v_mfma_f32_16x16x32_bf16 v[42:45], v[172:175], v[204:207], v[42:45]
	v_mfma_f32_16x16x32_bf16 v[30:33], v[164:167], v[212:215], v[30:33]
	v_mfma_f32_16x16x32_bf16 v[26:29], v[172:175], v[212:215], v[26:29]
	v_mfma_f32_16x16x32_bf16 v[14:17], v[164:167], v[220:223], v[14:17]
	v_mfma_f32_16x16x32_bf16 v[10:13], v[172:175], v[220:223], v[10:13]
	s_setprio 0
	s_setprio 1
	v_mfma_f32_16x16x32_bf16 v[54:57], v[176:179], v[192:195], v[54:57]
	v_mfma_f32_16x16x32_bf16 v[50:53], v[184:187], v[192:195], v[50:53]
	v_mfma_f32_16x16x32_bf16 v[38:41], v[176:179], v[200:203], v[38:41]
	v_mfma_f32_16x16x32_bf16 v[34:37], v[184:187], v[200:203], v[34:37]
	v_mfma_f32_16x16x32_bf16 v[22:25], v[176:179], v[208:211], v[22:25]
	v_mfma_f32_16x16x32_bf16 v[18:21], v[184:187], v[208:211], v[18:21]
	v_mfma_f32_16x16x32_bf16 v[6:9], v[176:179], v[216:219], v[6:9]
	v_mfma_f32_16x16x32_bf16 v[2:5], v[184:187], v[216:219], v[2:5]
	v_mfma_f32_16x16x32_bf16 v[54:57], v[180:183], v[196:199], v[54:57]
	v_mfma_f32_16x16x32_bf16 v[50:53], v[188:191], v[196:199], v[50:53]
	v_mfma_f32_16x16x32_bf16 v[38:41], v[180:183], v[204:207], v[38:41]
	v_mfma_f32_16x16x32_bf16 v[34:37], v[188:191], v[204:207], v[34:37]
	v_mfma_f32_16x16x32_bf16 v[22:25], v[180:183], v[212:215], v[22:25]
	v_mfma_f32_16x16x32_bf16 v[18:21], v[188:191], v[212:215], v[18:21]
	v_mfma_f32_16x16x32_bf16 v[6:9], v[180:183], v[220:223], v[6:9]
	v_mfma_f32_16x16x32_bf16 v[2:5], v[188:191], v[220:223], v[2:5]
	s_setprio 0
	s_barrier
	s_add_i32 s68, s68, 2
	s_add_u32 s28, s28, 0x100
	s_addc_u32 s29, s29, 0
	s_add_u32 s66, s66, 0x100
	s_addc_u32 s67, s67, 0
	s_cmp_gt_u32 s68, 13
	s_cbranch_scc1 .Lpeel_done_p6
	.p2align	6

; template <class Epi, class Sched, bool ALIGN_EPI = false, bool SP2 = false, bool AGM = false  >
; __device__ __forceinline__ void gemm_phase(PG8_LAS unsigned char* lds, const Gemm g, const Sched& S, const Epi& E) {
;     ...
;         const bool has_next = S.next(ui + 1, nxt);
;         const char* nA = has_next ? (const char*)g.A + (size_t)nxt.pm * tstepA : cA; const char* nB = has_next ? (const char*)g.Bt + (size_t)nxt.pn * tstep : cB;
;         for (int t = 0; t < nt; t += 2) {
;             const bool last = (t == nt - 2);
;             const char* a1 = cA + (size_t)(t + 1) * kstepA;
;             const char* a2 = last ? nA : cA + (size_t)(t + 2) * kstepA; const char* b2 = last ? nB : cB + (size_t)(t + 2) * kstep;
;             const char* a3 = a2 + kstepA; const char* b3 = b2 + kstep;
;     ...
; #pragma unroll
;         for (int a = 0; a < 2; ++a)
; #pragma unroll
;             for (int b = 0; b < 2; ++b)
; #pragma unroll
;                 for (int m = 0; m < 4; ++m)
; #pragma unroll
;                     for (int n = 0; n < 2; ++n) acc[a][b][m][n] = (f32x4){0.f, 0.f, 0.f, 0.f};
.LBB0_1067:
	s_add_u32 s30, s30, 0xb0080
	s_addc_u32 s31, s31, 0
	s_add_u32 s5, s34, 0x100
	v_mov_b32_e32 v2, 0
	s_addc_u32 s33, s35, 0
	s_mov_b32 s65, -2
	v_mov_b32_e32 v3, v2
	v_mov_b32_e32 v4, v2
	v_mov_b32_e32 v5, v2
	v_mov_b32_e32 v6, v2
	v_mov_b32_e32 v7, v2
	v_mov_b32_e32 v8, v2
	v_mov_b32_e32 v9, v2
	s_waitcnt vmcnt(0)
	v_mov_b32_e32 v18, v2
	v_mov_b32_e32 v19, v2
	v_mov_b32_e32 v20, v2
	v_mov_b32_e32 v21, v2
	v_mov_b32_e32 v22, v2
	v_mov_b32_e32 v23, v2
	v_mov_b32_e32 v24, v2
	v_mov_b32_e32 v25, v2
	v_mov_b32_e32 v34, v2
	v_mov_b32_e32 v35, v2
	v_mov_b32_e32 v36, v2
	v_mov_b32_e32 v37, v2
	v_mov_b32_e32 v38, v2
	v_mov_b32_e32 v39, v2
	v_mov_b32_e32 v40, v2
	v_mov_b32_e32 v41, v2
	v_mov_b32_e32 v50, v2
	v_mov_b32_e32 v51, v2
	v_mov_b32_e32 v52, v2
	v_mov_b32_e32 v53, v2
	v_mov_b32_e32 v54, v2
	v_mov_b32_e32 v55, v2
	v_mov_b32_e32 v56, v2
	v_mov_b32_e32 v57, v2
	v_mov_b32_e32 v10, v2
	v_mov_b32_e32 v11, v2
	v_mov_b32_e32 v12, v2
	v_mov_b32_e32 v13, v2
	v_mov_b32_e32 v14, v2
	v_mov_b32_e32 v15, v2
	v_mov_b32_e32 v16, v2
	v_mov_b32_e32 v17, v2
	v_mov_b32_e32 v26, v2
	v_mov_b32_e32 v27, v2
	s_waitcnt lgkmcnt(0)
	v_mov_b32_e32 v28, v2
	v_mov_b32_e32 v29, v2
	v_mov_b32_e32 v30, v2
	v_mov_b32_e32 v31, v2
	v_mov_b32_e32 v32, v2
	v_mov_b32_e32 v33, v2
	v_mov_b32_e32 v42, v2
	v_mov_b32_e32 v43, v2
	v_mov_b32_e32 v44, v2
	v_mov_b32_e32 v45, v2
	v_mov_b32_e32 v46, v2
	v_mov_b32_e32 v47, v2
	v_mov_b32_e32 v48, v2
	v_mov_b32_e32 v49, v2
	v_mov_b32_e32 v58, v2
	v_mov_b32_e32 v59, v2
	v_mov_b32_e32 v60, v2
	v_mov_b32_e32 v61, v2
	v_mov_b32_e32 v62, v2
	v_mov_b32_e32 v63, v2
	v_mov_b32_e32 v64, v2
	v_mov_b32_e32 v65, v2
	v_mov_b32_e32 v66, v2
	v_mov_b32_e32 v67, v2
	v_mov_b32_e32 v68, v2
	v_mov_b32_e32 v69, v2
	v_mov_b32_e32 v70, v2
	v_mov_b32_e32 v71, v2
	v_mov_b32_e32 v72, v2
	v_mov_b32_e32 v73, v2
	v_mov_b32_e32 v82, v2
	v_mov_b32_e32 v83, v2
	v_mov_b32_e32 v84, v2
	v_mov_b32_e32 v85, v2
	v_mov_b32_e32 v86, v2
	v_mov_b32_e32 v87, v2
	v_mov_b32_e32 v88, v2
	v_mov_b32_e32 v89, v2
	v_mov_b32_e32 v98, v2
	v_mov_b32_e32 v99, v2
	v_mov_b32_e32 v100, v2
	v_mov_b32_e32 v101, v2
	v_mov_b32_e32 v102, v2
	v_mov_b32_e32 v103, v2
	v_mov_b32_e32 v104, v2
	v_mov_b32_e32 v105, v2
	v_mov_b32_e32 v114, v2
	v_mov_b32_e32 v115, v2
	v_mov_b32_e32 v116, v2
	v_mov_b32_e32 v117, v2
	v_mov_b32_e32 v118, v2
	v_mov_b32_e32 v119, v2
	v_mov_b32_e32 v120, v2
	v_mov_b32_e32 v121, v2
	v_mov_b32_e32 v74, v2
	v_mov_b32_e32 v75, v2
	v_mov_b32_e32 v76, v2
	v_mov_b32_e32 v77, v2
	v_mov_b32_e32 v78, v2
	v_mov_b32_e32 v79, v2
	v_mov_b32_e32 v80, v2
	v_mov_b32_e32 v81, v2
	v_mov_b32_e32 v90, v2
	v_mov_b32_e32 v91, v2
	v_mov_b32_e32 v92, v2
	v_mov_b32_e32 v93, v2
	v_mov_b32_e32 v94, v2
	v_mov_b32_e32 v95, v2
	v_mov_b32_e32 v96, v2
	v_mov_b32_e32 v97, v2
	v_mov_b32_e32 v106, v2
	v_mov_b32_e32 v107, v2
	v_mov_b32_e32 v108, v2
	v_mov_b32_e32 v109, v2
	v_mov_b32_e32 v110, v2
	v_mov_b32_e32 v111, v2
	v_mov_b32_e32 v112, v2
	v_mov_b32_e32 v113, v2
	v_mov_b32_e32 v122, v2
	v_mov_b32_e32 v123, v2
	v_mov_b32_e32 v124, v2
	v_mov_b32_e32 v125, v2
	v_mov_b32_e32 v126, v2
	v_mov_b32_e32 v127, v2
	v_mov_b32_e32 v128, v2
	v_mov_b32_e32 v129, v2
	.p2align	6
